# v114 + RWKV scanner v5: state kept as (row0,row1) pairs per column, per-column operands broadcast by op_sel -- the four per-step lane-sum adds disappear
# speedup vs baseline: 1.0026x; 1.0026x over previous
.Lscan_q4:
	s_waitcnt lgkmcnt(0)
	v_pk_mul_f32 v[16:17], v[0:1], v[32:33] op_sel_hi:[1,0]
	v_pk_mul_f32 v[20:21], v[0:1], v[40:41] op_sel_hi:[1,0]
	ds_read_b128 v[76:79], v130 offset:256
	v_pk_fma_f32 v[16:17], v[2:3], v[32:33], v[16:17] op_sel:[0,1,0]
	v_pk_fma_f32 v[20:21], v[2:3], v[40:41], v[20:21] op_sel:[0,1,0]
	ds_read_b128 v[80:83], v130 offset:272
	v_pk_fma_f32 v[16:17], v[4:5], v[34:35], v[16:17] op_sel_hi:[1,0,1]
	v_pk_fma_f32 v[20:21], v[4:5], v[42:43], v[20:21] op_sel_hi:[1,0,1]
	ds_read_b128 v[90:93], v130 offset:4352
	v_pk_fma_f32 v[16:17], v[6:7], v[34:35], v[16:17] op_sel:[0,1,0]
	v_pk_fma_f32 v[20:21], v[6:7], v[42:43], v[20:21] op_sel:[0,1,0]
	ds_read_b128 v[94:97], v130 offset:4368
	v_pk_fma_f32 v[16:17], v[8:9], v[36:37], v[16:17] op_sel_hi:[1,0,1]
	v_pk_fma_f32 v[20:21], v[8:9], v[44:45], v[20:21] op_sel_hi:[1,0,1]
	ds_read_b128 v[112:115], v130 offset:12544
	v_pk_fma_f32 v[16:17], v[10:11], v[36:37], v[16:17] op_sel:[0,1,0]
	v_pk_fma_f32 v[20:21], v[10:11], v[44:45], v[20:21] op_sel:[0,1,0]
	ds_read_b128 v[116:119], v130 offset:12560
	v_pk_fma_f32 v[16:17], v[12:13], v[38:39], v[16:17] op_sel_hi:[1,0,1]
	v_pk_fma_f32 v[20:21], v[12:13], v[46:47], v[20:21] op_sel_hi:[1,0,1]
	ds_read_b128 v[120:123], v130 offset:16640
	v_pk_fma_f32 v[16:17], v[14:15], v[38:39], v[16:17] op_sel:[0,1,0]
	v_pk_fma_f32 v[20:21], v[14:15], v[46:47], v[20:21] op_sel:[0,1,0]
	ds_read_b128 v[124:127], v130 offset:16656
	ds_read_b128 v[98:101], v130 offset:8448
	ds_read_b128 v[102:105], v130 offset:8464
	ds_read2_b64 v[106:109], v131 offset0:64 offset1:96
	ds_read2_b64 v[144:147], v85 offset0:4 offset1:6
	v_pk_mul_f32 v[164:165], v[72:73], v[64:65] op_sel_hi:[1,0]
	v_add_f32_dpp v16, v16, v16 quad_perm:[1,0,3,2] row_mask:0xf bank_mask:0xf bound_ctrl:1
	v_add_f32_dpp v17, v17, v17 quad_perm:[1,0,3,2] row_mask:0xf bank_mask:0xf bound_ctrl:1
	v_pk_fma_f32 v[176:177], v[72:73], v[140:141], v[20:21] op_sel:[0,1,0]
	v_add_f32_dpp v16, v16, v16 quad_perm:[2,3,0,1] row_mask:0xf bank_mask:0xf bound_ctrl:1
	v_add_f32_dpp v17, v17, v17 quad_perm:[2,3,0,1] row_mask:0xf bank_mask:0xf bound_ctrl:1
	v_pk_mul_f32 v[166:167], v[72:73], v[64:65] op_sel:[0,1]
	v_add_f32_dpp v16, v16, v16 row_half_mirror row_mask:0xf bank_mask:0xf bound_ctrl:1
	v_add_f32_dpp v17, v17, v17 row_half_mirror row_mask:0xf bank_mask:0xf bound_ctrl:1
	v_pk_mul_f32 v[168:169], v[72:73], v[66:67] op_sel_hi:[1,0]
	v_pk_mul_f32 v[170:171], v[72:73], v[66:67] op_sel:[0,1]
	v_pk_fma_f32 v[164:165], v[16:17], v[56:57], v[164:165] op_sel_hi:[1,0,1]
	v_pk_fma_f32 v[166:167], v[16:17], v[56:57], v[166:167] op_sel:[0,1,0]
	v_pk_fma_f32 v[168:169], v[16:17], v[58:59], v[168:169] op_sel_hi:[1,0,1]
	v_pk_fma_f32 v[170:171], v[16:17], v[58:59], v[170:171] op_sel:[0,1,0]
	v_pk_fma_f32 v[0:1], v[0:1], v[48:49], v[164:165] op_sel_hi:[1,0,1]
	v_pk_fma_f32 v[2:3], v[2:3], v[48:49], v[166:167] op_sel:[0,1,0]
	v_pk_fma_f32 v[4:5], v[4:5], v[50:51], v[168:169] op_sel_hi:[1,0,1]
	v_pk_fma_f32 v[6:7], v[6:7], v[50:51], v[170:171] op_sel:[0,1,0]
	v_pk_mul_f32 v[164:165], v[72:73], v[68:69] op_sel_hi:[1,0]
	v_pk_mul_f32 v[166:167], v[72:73], v[68:69] op_sel:[0,1]
	v_pk_mul_f32 v[168:169], v[72:73], v[70:71] op_sel_hi:[1,0]
	v_pk_mul_f32 v[170:171], v[72:73], v[70:71] op_sel:[0,1]
	v_pk_fma_f32 v[164:165], v[16:17], v[60:61], v[164:165] op_sel_hi:[1,0,1]
	v_pk_fma_f32 v[166:167], v[16:17], v[60:61], v[166:167] op_sel:[0,1,0]
	v_pk_fma_f32 v[168:169], v[16:17], v[62:63], v[168:169] op_sel_hi:[1,0,1]
	v_pk_fma_f32 v[170:171], v[16:17], v[62:63], v[170:171] op_sel:[0,1,0]
	v_pk_fma_f32 v[8:9], v[8:9], v[52:53], v[164:165] op_sel_hi:[1,0,1]
	v_pk_fma_f32 v[10:11], v[10:11], v[52:53], v[166:167] op_sel:[0,1,0]
	v_pk_fma_f32 v[12:13], v[12:13], v[54:55], v[168:169] op_sel_hi:[1,0,1]
	v_pk_fma_f32 v[14:15], v[14:15], v[54:55], v[170:171] op_sel:[0,1,0]
	v_pk_fma_f32 v[176:177], v[16:17], v[140:141], v[176:177] op_sel_hi:[1,0,1]
	s_waitcnt lgkmcnt(0)
	v_pk_mul_f32 v[16:17], v[0:1], v[76:77] op_sel_hi:[1,0]
	v_pk_mul_f32 v[20:21], v[0:1], v[90:91] op_sel_hi:[1,0]
	ds_read_b128 v[32:35], v130 offset:512
	v_pk_fma_f32 v[16:17], v[2:3], v[76:77], v[16:17] op_sel:[0,1,0]
	v_pk_fma_f32 v[20:21], v[2:3], v[90:91], v[20:21] op_sel:[0,1,0]
	ds_read_b128 v[36:39], v130 offset:528
	v_pk_fma_f32 v[16:17], v[4:5], v[78:79], v[16:17] op_sel_hi:[1,0,1]
	v_pk_fma_f32 v[20:21], v[4:5], v[92:93], v[20:21] op_sel_hi:[1,0,1]
	ds_read_b128 v[40:43], v130 offset:4608
	v_pk_fma_f32 v[16:17], v[6:7], v[78:79], v[16:17] op_sel:[0,1,0]
	v_pk_fma_f32 v[20:21], v[6:7], v[92:93], v[20:21] op_sel:[0,1,0]
	ds_read_b128 v[44:47], v130 offset:4624
	v_pk_fma_f32 v[16:17], v[8:9], v[80:81], v[16:17] op_sel_hi:[1,0,1]
	v_pk_fma_f32 v[20:21], v[8:9], v[94:95], v[20:21] op_sel_hi:[1,0,1]
	ds_read_b128 v[56:59], v130 offset:12800
	v_pk_fma_f32 v[16:17], v[10:11], v[80:81], v[16:17] op_sel:[0,1,0]
	v_pk_fma_f32 v[20:21], v[10:11], v[94:95], v[20:21] op_sel:[0,1,0]
	ds_read_b128 v[60:63], v130 offset:12816
	v_pk_fma_f32 v[16:17], v[12:13], v[82:83], v[16:17] op_sel_hi:[1,0,1]
	v_pk_fma_f32 v[20:21], v[12:13], v[96:97], v[20:21] op_sel_hi:[1,0,1]
	ds_read_b128 v[64:67], v130 offset:16896
	v_pk_fma_f32 v[16:17], v[14:15], v[82:83], v[16:17] op_sel:[0,1,0]
	v_pk_fma_f32 v[20:21], v[14:15], v[96:97], v[20:21] op_sel:[0,1,0]
	ds_read_b128 v[68:71], v130 offset:16912
	ds_read_b128 v[48:51], v130 offset:8704
	ds_read_b128 v[52:55], v130 offset:8720
	v_pk_mul_f32 v[164:165], v[74:75], v[120:121] op_sel_hi:[1,0]
	v_add_f32_dpp v16, v16, v16 quad_perm:[1,0,3,2] row_mask:0xf bank_mask:0xf bound_ctrl:1
	v_add_f32_dpp v17, v17, v17 quad_perm:[1,0,3,2] row_mask:0xf bank_mask:0xf bound_ctrl:1
	v_pk_fma_f32 v[178:179], v[74:75], v[142:143], v[20:21] op_sel:[0,1,0]
	v_add_f32_dpp v16, v16, v16 quad_perm:[2,3,0,1] row_mask:0xf bank_mask:0xf bound_ctrl:1
	v_add_f32_dpp v17, v17, v17 quad_perm:[2,3,0,1] row_mask:0xf bank_mask:0xf bound_ctrl:1
	v_pk_mul_f32 v[166:167], v[74:75], v[120:121] op_sel:[0,1]
	v_add_f32_dpp v16, v16, v16 row_half_mirror row_mask:0xf bank_mask:0xf bound_ctrl:1
	v_add_f32_dpp v17, v17, v17 row_half_mirror row_mask:0xf bank_mask:0xf bound_ctrl:1
	v_pk_mul_f32 v[168:169], v[74:75], v[122:123] op_sel_hi:[1,0]
	v_pk_mul_f32 v[170:171], v[74:75], v[122:123] op_sel:[0,1]
	v_pk_fma_f32 v[164:165], v[16:17], v[112:113], v[164:165] op_sel_hi:[1,0,1]
	v_pk_fma_f32 v[166:167], v[16:17], v[112:113], v[166:167] op_sel:[0,1,0]
	v_pk_fma_f32 v[168:169], v[16:17], v[114:115], v[168:169] op_sel_hi:[1,0,1]
	v_pk_fma_f32 v[170:171], v[16:17], v[114:115], v[170:171] op_sel:[0,1,0]
	v_pk_fma_f32 v[0:1], v[0:1], v[98:99], v[164:165] op_sel_hi:[1,0,1]
	v_pk_fma_f32 v[2:3], v[2:3], v[98:99], v[166:167] op_sel:[0,1,0]
	v_pk_fma_f32 v[4:5], v[4:5], v[100:101], v[168:169] op_sel_hi:[1,0,1]
	v_pk_fma_f32 v[6:7], v[6:7], v[100:101], v[170:171] op_sel:[0,1,0]
	v_pk_mul_f32 v[164:165], v[74:75], v[124:125] op_sel_hi:[1,0]
	v_pk_mul_f32 v[166:167], v[74:75], v[124:125] op_sel:[0,1]
	v_pk_mul_f32 v[168:169], v[74:75], v[126:127] op_sel_hi:[1,0]
	v_pk_mul_f32 v[170:171], v[74:75], v[126:127] op_sel:[0,1]
	v_pk_fma_f32 v[164:165], v[16:17], v[116:117], v[164:165] op_sel_hi:[1,0,1]
	v_pk_fma_f32 v[166:167], v[16:17], v[116:117], v[166:167] op_sel:[0,1,0]
	v_pk_fma_f32 v[168:169], v[16:17], v[118:119], v[168:169] op_sel_hi:[1,0,1]
	v_pk_fma_f32 v[170:171], v[16:17], v[118:119], v[170:171] op_sel:[0,1,0]
	v_pk_fma_f32 v[8:9], v[8:9], v[102:103], v[164:165] op_sel_hi:[1,0,1]
	v_pk_fma_f32 v[10:11], v[10:11], v[102:103], v[166:167] op_sel:[0,1,0]
	v_pk_fma_f32 v[12:13], v[12:13], v[104:105], v[168:169] op_sel_hi:[1,0,1]
	v_pk_fma_f32 v[14:15], v[14:15], v[104:105], v[170:171] op_sel:[0,1,0]
	v_pk_fma_f32 v[178:179], v[16:17], v[142:143], v[178:179] op_sel_hi:[1,0,1]
	s_waitcnt lgkmcnt(0)
	v_pk_mul_f32 v[16:17], v[0:1], v[32:33] op_sel_hi:[1,0]
	v_pk_mul_f32 v[20:21], v[0:1], v[40:41] op_sel_hi:[1,0]
	ds_read_b128 v[76:79], v130 offset:768
	v_pk_fma_f32 v[16:17], v[2:3], v[32:33], v[16:17] op_sel:[0,1,0]
	v_pk_fma_f32 v[20:21], v[2:3], v[40:41], v[20:21] op_sel:[0,1,0]
	ds_read_b128 v[80:83], v130 offset:784
	v_pk_fma_f32 v[16:17], v[4:5], v[34:35], v[16:17] op_sel_hi:[1,0,1]
	v_pk_fma_f32 v[20:21], v[4:5], v[42:43], v[20:21] op_sel_hi:[1,0,1]
	ds_read_b128 v[90:93], v130 offset:4864
	v_pk_fma_f32 v[16:17], v[6:7], v[34:35], v[16:17] op_sel:[0,1,0]
	v_pk_fma_f32 v[20:21], v[6:7], v[42:43], v[20:21] op_sel:[0,1,0]
	ds_read_b128 v[94:97], v130 offset:4880
	v_pk_fma_f32 v[16:17], v[8:9], v[36:37], v[16:17] op_sel_hi:[1,0,1]
	v_pk_fma_f32 v[20:21], v[8:9], v[44:45], v[20:21] op_sel_hi:[1,0,1]
	ds_read_b128 v[112:115], v130 offset:13056
	v_pk_fma_f32 v[16:17], v[10:11], v[36:37], v[16:17] op_sel:[0,1,0]
	v_pk_fma_f32 v[20:21], v[10:11], v[44:45], v[20:21] op_sel:[0,1,0]
	ds_read_b128 v[116:119], v130 offset:13072
	v_pk_fma_f32 v[16:17], v[12:13], v[38:39], v[16:17] op_sel_hi:[1,0,1]
	v_pk_fma_f32 v[20:21], v[12:13], v[46:47], v[20:21] op_sel_hi:[1,0,1]
	ds_read_b128 v[120:123], v130 offset:17152
	v_pk_fma_f32 v[16:17], v[14:15], v[38:39], v[16:17] op_sel:[0,1,0]
	v_pk_fma_f32 v[20:21], v[14:15], v[46:47], v[20:21] op_sel:[0,1,0]
	ds_read_b128 v[124:127], v130 offset:17168
	ds_read_b128 v[98:101], v130 offset:8960
	ds_read_b128 v[102:105], v130 offset:8976
	ds_read2_b64 v[72:75], v131 offset0:128 offset1:160
	ds_read2_b64 v[140:143], v85 offset0:8 offset1:10
	v_pk_mul_f32 v[164:165], v[106:107], v[64:65] op_sel_hi:[1,0]
	v_add_f32_dpp v16, v16, v16 quad_perm:[1,0,3,2] row_mask:0xf bank_mask:0xf bound_ctrl:1
	v_add_f32_dpp v17, v17, v17 quad_perm:[1,0,3,2] row_mask:0xf bank_mask:0xf bound_ctrl:1
	v_pk_fma_f32 v[180:181], v[106:107], v[144:145], v[20:21] op_sel:[0,1,0]
	v_add_f32_dpp v16, v16, v16 quad_perm:[2,3,0,1] row_mask:0xf bank_mask:0xf bound_ctrl:1
	v_add_f32_dpp v17, v17, v17 quad_perm:[2,3,0,1] row_mask:0xf bank_mask:0xf bound_ctrl:1
	v_pk_mul_f32 v[166:167], v[106:107], v[64:65] op_sel:[0,1]
	v_add_f32_dpp v16, v16, v16 row_half_mirror row_mask:0xf bank_mask:0xf bound_ctrl:1
	v_add_f32_dpp v17, v17, v17 row_half_mirror row_mask:0xf bank_mask:0xf bound_ctrl:1
	v_pk_mul_f32 v[168:169], v[106:107], v[66:67] op_sel_hi:[1,0]
	v_pk_mul_f32 v[170:171], v[106:107], v[66:67] op_sel:[0,1]
	v_pk_fma_f32 v[164:165], v[16:17], v[56:57], v[164:165] op_sel_hi:[1,0,1]
	v_pk_fma_f32 v[166:167], v[16:17], v[56:57], v[166:167] op_sel:[0,1,0]
	v_pk_fma_f32 v[168:169], v[16:17], v[58:59], v[168:169] op_sel_hi:[1,0,1]
	v_pk_fma_f32 v[170:171], v[16:17], v[58:59], v[170:171] op_sel:[0,1,0]
	v_pk_fma_f32 v[0:1], v[0:1], v[48:49], v[164:165] op_sel_hi:[1,0,1]
	v_pk_fma_f32 v[2:3], v[2:3], v[48:49], v[166:167] op_sel:[0,1,0]
	v_pk_fma_f32 v[4:5], v[4:5], v[50:51], v[168:169] op_sel_hi:[1,0,1]
	v_pk_fma_f32 v[6:7], v[6:7], v[50:51], v[170:171] op_sel:[0,1,0]
	v_pk_mul_f32 v[164:165], v[106:107], v[68:69] op_sel_hi:[1,0]
	v_pk_mul_f32 v[166:167], v[106:107], v[68:69] op_sel:[0,1]
	v_pk_mul_f32 v[168:169], v[106:107], v[70:71] op_sel_hi:[1,0]
	v_pk_mul_f32 v[170:171], v[106:107], v[70:71] op_sel:[0,1]
	v_pk_fma_f32 v[164:165], v[16:17], v[60:61], v[164:165] op_sel_hi:[1,0,1]
	v_pk_fma_f32 v[166:167], v[16:17], v[60:61], v[166:167] op_sel:[0,1,0]
	v_pk_fma_f32 v[168:169], v[16:17], v[62:63], v[168:169] op_sel_hi:[1,0,1]
	v_pk_fma_f32 v[170:171], v[16:17], v[62:63], v[170:171] op_sel:[0,1,0]
	v_pk_fma_f32 v[8:9], v[8:9], v[52:53], v[164:165] op_sel_hi:[1,0,1]
	v_pk_fma_f32 v[10:11], v[10:11], v[52:53], v[166:167] op_sel:[0,1,0]
	v_pk_fma_f32 v[12:13], v[12:13], v[54:55], v[168:169] op_sel_hi:[1,0,1]
	v_pk_fma_f32 v[14:15], v[14:15], v[54:55], v[170:171] op_sel:[0,1,0]
	v_pk_fma_f32 v[180:181], v[16:17], v[144:145], v[180:181] op_sel_hi:[1,0,1]
	s_waitcnt lgkmcnt(0)
	v_pk_mul_f32 v[16:17], v[0:1], v[76:77] op_sel_hi:[1,0]
	v_pk_mul_f32 v[20:21], v[0:1], v[90:91] op_sel_hi:[1,0]
	ds_read_b128 v[32:35], v130 offset:1024
	v_pk_fma_f32 v[16:17], v[2:3], v[76:77], v[16:17] op_sel:[0,1,0]
	v_pk_fma_f32 v[20:21], v[2:3], v[90:91], v[20:21] op_sel:[0,1,0]
	ds_read_b128 v[36:39], v130 offset:1040
	v_pk_fma_f32 v[16:17], v[4:5], v[78:79], v[16:17] op_sel_hi:[1,0,1]
	v_pk_fma_f32 v[20:21], v[4:5], v[92:93], v[20:21] op_sel_hi:[1,0,1]
	ds_read_b128 v[40:43], v130 offset:5120
	v_pk_fma_f32 v[16:17], v[6:7], v[78:79], v[16:17] op_sel:[0,1,0]
	v_pk_fma_f32 v[20:21], v[6:7], v[92:93], v[20:21] op_sel:[0,1,0]
	ds_read_b128 v[44:47], v130 offset:5136
	v_pk_fma_f32 v[16:17], v[8:9], v[80:81], v[16:17] op_sel_hi:[1,0,1]
	v_pk_fma_f32 v[20:21], v[8:9], v[94:95], v[20:21] op_sel_hi:[1,0,1]
	ds_read_b128 v[56:59], v130 offset:13312
	v_pk_fma_f32 v[16:17], v[10:11], v[80:81], v[16:17] op_sel:[0,1,0]
	v_pk_fma_f32 v[20:21], v[10:11], v[94:95], v[20:21] op_sel:[0,1,0]
	ds_read_b128 v[60:63], v130 offset:13328
	v_pk_fma_f32 v[16:17], v[12:13], v[82:83], v[16:17] op_sel_hi:[1,0,1]
	v_pk_fma_f32 v[20:21], v[12:13], v[96:97], v[20:21] op_sel_hi:[1,0,1]
	ds_read_b128 v[64:67], v130 offset:17408
	v_pk_fma_f32 v[16:17], v[14:15], v[82:83], v[16:17] op_sel:[0,1,0]
	v_pk_fma_f32 v[20:21], v[14:15], v[96:97], v[20:21] op_sel:[0,1,0]
	ds_read_b128 v[68:71], v130 offset:17424
	ds_read_b128 v[48:51], v130 offset:9216
	ds_read_b128 v[52:55], v130 offset:9232
	v_pk_mul_f32 v[164:165], v[108:109], v[120:121] op_sel_hi:[1,0]
	v_add_f32_dpp v16, v16, v16 quad_perm:[1,0,3,2] row_mask:0xf bank_mask:0xf bound_ctrl:1
	v_add_f32_dpp v17, v17, v17 quad_perm:[1,0,3,2] row_mask:0xf bank_mask:0xf bound_ctrl:1
	v_pk_fma_f32 v[182:183], v[108:109], v[146:147], v[20:21] op_sel:[0,1,0]
	v_add_f32_dpp v16, v16, v16 quad_perm:[2,3,0,1] row_mask:0xf bank_mask:0xf bound_ctrl:1
	v_add_f32_dpp v17, v17, v17 quad_perm:[2,3,0,1] row_mask:0xf bank_mask:0xf bound_ctrl:1
	v_pk_mul_f32 v[166:167], v[108:109], v[120:121] op_sel:[0,1]
	v_add_f32_dpp v16, v16, v16 row_half_mirror row_mask:0xf bank_mask:0xf bound_ctrl:1
	v_add_f32_dpp v17, v17, v17 row_half_mirror row_mask:0xf bank_mask:0xf bound_ctrl:1
	v_pk_mul_f32 v[168:169], v[108:109], v[122:123] op_sel_hi:[1,0]
	v_pk_mul_f32 v[170:171], v[108:109], v[122:123] op_sel:[0,1]
	v_pk_fma_f32 v[164:165], v[16:17], v[112:113], v[164:165] op_sel_hi:[1,0,1]
	v_pk_fma_f32 v[166:167], v[16:17], v[112:113], v[166:167] op_sel:[0,1,0]
	v_pk_fma_f32 v[168:169], v[16:17], v[114:115], v[168:169] op_sel_hi:[1,0,1]
	v_pk_fma_f32 v[170:171], v[16:17], v[114:115], v[170:171] op_sel:[0,1,0]
	v_pk_fma_f32 v[0:1], v[0:1], v[98:99], v[164:165] op_sel_hi:[1,0,1]
	v_pk_fma_f32 v[2:3], v[2:3], v[98:99], v[166:167] op_sel:[0,1,0]
	v_pk_fma_f32 v[4:5], v[4:5], v[100:101], v[168:169] op_sel_hi:[1,0,1]
	v_pk_fma_f32 v[6:7], v[6:7], v[100:101], v[170:171] op_sel:[0,1,0]
	v_pk_mul_f32 v[164:165], v[108:109], v[124:125] op_sel_hi:[1,0]
	v_pk_mul_f32 v[166:167], v[108:109], v[124:125] op_sel:[0,1]
	v_pk_mul_f32 v[168:169], v[108:109], v[126:127] op_sel_hi:[1,0]
	v_pk_mul_f32 v[170:171], v[108:109], v[126:127] op_sel:[0,1]
	v_pk_fma_f32 v[164:165], v[16:17], v[116:117], v[164:165] op_sel_hi:[1,0,1]
	v_pk_fma_f32 v[166:167], v[16:17], v[116:117], v[166:167] op_sel:[0,1,0]
	v_pk_fma_f32 v[168:169], v[16:17], v[118:119], v[168:169] op_sel_hi:[1,0,1]
	v_pk_fma_f32 v[170:171], v[16:17], v[118:119], v[170:171] op_sel:[0,1,0]
	v_pk_fma_f32 v[8:9], v[8:9], v[102:103], v[164:165] op_sel_hi:[1,0,1]
	v_pk_fma_f32 v[10:11], v[10:11], v[102:103], v[166:167] op_sel:[0,1,0]
	v_pk_fma_f32 v[12:13], v[12:13], v[104:105], v[168:169] op_sel_hi:[1,0,1]
	v_pk_fma_f32 v[14:15], v[14:15], v[104:105], v[170:171] op_sel:[0,1,0]
	v_pk_fma_f32 v[182:183], v[16:17], v[146:147], v[182:183] op_sel_hi:[1,0,1]
	v_add_f32_dpp v176, v176, v176 row_half_mirror row_mask:0xf bank_mask:0x5
	v_add_f32_dpp v176, v180, v180 row_half_mirror row_mask:0xf bank_mask:0xa
	v_add_f32_dpp v177, v177, v177 row_half_mirror row_mask:0xf bank_mask:0x5
	v_add_f32_dpp v177, v181, v181 row_half_mirror row_mask:0xf bank_mask:0xa
	v_add_f32_dpp v178, v178, v178 row_half_mirror row_mask:0xf bank_mask:0x5
	v_add_f32_dpp v178, v182, v182 row_half_mirror row_mask:0xf bank_mask:0xa
	v_add_f32_dpp v179, v179, v179 row_half_mirror row_mask:0xf bank_mask:0x5
	v_add_f32_dpp v179, v183, v183 row_half_mirror row_mask:0xf bank_mask:0xa
	v_cndmask_b32_e64 v16, v178, v176, s[46:47]
	v_cndmask_b32_e64 v17, v176, v178, s[46:47]
	v_cndmask_b32_e64 v18, v179, v177, s[46:47]
	v_cndmask_b32_e64 v19, v177, v179, s[46:47]
	v_add_u32_e32 v130, 0x400, v130
	v_add_f32_dpp v176, v17, v16 quad_perm:[2,3,0,1] row_mask:0xf bank_mask:0xf bound_ctrl:1
	v_add_u32_e32 v131, 0x400, v131
	v_add_f32_dpp v177, v19, v18 quad_perm:[2,3,0,1] row_mask:0xf bank_mask:0xf bound_ctrl:1
	v_add_u32_e32 v85, 64, v85
	v_cndmask_b32_e64 v16, v177, v176, s[48:49]
	v_cndmask_b32_e64 v17, v176, v177, s[48:49]
	s_add_i32 s0, s0, -1
	s_cmp_lg_u32 s0, 0
	v_add_f32_dpp v18, v17, v16 quad_perm:[1,0,3,2] row_mask:0xf bank_mask:0xf bound_ctrl:1
	s_nop 0
	ds_write_b32 v86, v18
	v_add_u32_e32 v86, 0x400, v86
	s_cbranch_scc1 .Lscan_q4
	s_xor_b32 s1, s1, 0x8200
	s_add_i32 s2, s2, -1
	s_waitcnt lgkmcnt(0)
	s_barrier
	s_cmp_lg_u32 s2, 0
	s_cbranch_scc1 .Lscan_chunk
	s_branch .LBB0_627
